# speedup vs baseline: 1.0072x; 1.0007x over previous
;   __device__ __forceinline__ const float* in(int i) const { return ((const float* const*)(ws + OFF_TBL))[i]; }
; __device__ __forceinline__ float logsig(float x) { return fminf(x, 0.f) - __logf(1.f + __expf(-fabsf(x))); }
; __device__ void gate_scan(const Ctx& p) {
;     ...
;   for (int bh = blockIdx.x; bh < 8; bh += gridDim.x) {
;     const int b = bh >> 2, h = bh & 3;
;     float ip[16], lf[16];
;     const float bi = p.in(20)[h], bf = p.in(20)[4 + h];
;     float run = 0.f;
; #pragma unroll
;     for (int e = 0; e < 16; ++e) {
;       long tok = (long)b * SEQ + tid * 16 + e;
;       float si = bi, sf = bf;
; #pragma unroll
;       for (int cgp = 0; cgp < 8; ++cgp) {
;         si += gpart[((long)cgp * NTOK + tok) * 8 + h];
;         sf += gpart[((long)cgp * NTOK + tok) * 8 + 4 + h];
;       }
;       ip[e] = si;
;       run += logsig(sf);
;       lf[e] = run;
;     }
.LBB0_34:
	global_load_dwordx2 v[8:9], v[6:7], off
	s_ashr_i32 s0, s61, 2
	s_and_b32 s1, s61, 3
	s_lshl_b32 s52, s1, 2
	s_ashr_i32 s1, s0, 31
	s_add_u32 s38, s46, s52
	s_addc_u32 s39, s47, 0
	s_lshl_b64 s[0:1], s[0:1], 18
	s_add_u32 s0, s38, s0
	s_addc_u32 s1, s39, s1
	s_waitcnt vmcnt(0) lgkmcnt(0)
	v_lshl_add_u64 v[8:9], v[8:9], 0, s[52:53]
	global_load_dword v5, v[8:9], off
	global_load_dword v58, v[8:9], off offset:16
	v_lshl_add_u64 v[8:9], s[0:1], 0, v[2:3]
	s_mov_b32 s0, 0x80000
	v_add_co_u32_e64 v20, s[0:1], s0, v8
	global_load_dword v30, v[8:9], off
	global_load_dword v10, v[8:9], off offset:16
	v_addc_co_u32_e64 v21, s[0:1], 0, v9, s[0:1]
	global_load_dword v31, v[20:21], off
	global_load_dword v11, v[20:21], off offset:16
	s_waitcnt vmcnt(0) lgkmcnt(0)
	v_add_f32_e32 v10, v58, v10
	v_add_f32_e32 v12, v10, v11
	v_add_co_u32_e64 v10, s[0:1], s40, v8
	s_nop 1
	v_addc_co_u32_e64 v11, s[0:1], 0, v9, s[0:1]
	global_load_dword v32, v[10:11], off
	global_load_dword v13, v[10:11], off offset:16
	s_mov_b32 s0, 0x180000
	s_waitcnt vmcnt(0) lgkmcnt(0)
	v_add_f32_e32 v14, v12, v13
	v_add_co_u32_e64 v12, s[0:1], s0, v8
	s_nop 1
	v_addc_co_u32_e64 v13, s[0:1], 0, v9, s[0:1]
	global_load_dword v33, v[12:13], off
	global_load_dword v15, v[12:13], off offset:16
	s_mov_b32 s0, 0x200000
	s_waitcnt vmcnt(0) lgkmcnt(0)
	v_add_f32_e32 v16, v14, v15
	v_add_co_u32_e64 v14, s[0:1], s0, v8
	s_nop 1
	v_addc_co_u32_e64 v15, s[0:1], 0, v9, s[0:1]
	global_load_dword v35, v[14:15], off
	global_load_dword v17, v[14:15], off offset:16
	s_mov_b32 s0, 0x280000
	s_waitcnt vmcnt(0) lgkmcnt(0)
	v_add_f32_e32 v18, v16, v17
	v_add_co_u32_e64 v16, s[0:1], s0, v8
	s_nop 1
	v_addc_co_u32_e64 v17, s[0:1], 0, v9, s[0:1]
	global_load_dword v36, v[16:17], off
	global_load_dword v19, v[16:17], off offset:16
	s_mov_b32 s0, 0x300000
	s_waitcnt vmcnt(0) lgkmcnt(0)
	v_add_f32_e32 v22, v18, v19
	v_add_co_u32_e64 v18, s[0:1], s0, v8
	s_nop 1
	v_addc_co_u32_e64 v19, s[0:1], 0, v9, s[0:1]
	global_load_dword v37, v[18:19], off
	global_load_dword v23, v[18:19], off offset:16
	s_mov_b32 s0, 0x380000
	s_waitcnt vmcnt(0) lgkmcnt(0)
	v_add_f32_e32 v34, v22, v23
	v_add_co_u32_e64 v22, s[0:1], s0, v8
	s_nop 1
	v_addc_co_u32_e64 v23, s[0:1], 0, v9, s[0:1]
	global_load_dword v38, v[22:23], off
	global_load_dword v39, v[22:23], off offset:16
	s_waitcnt vmcnt(0) lgkmcnt(0)
	v_add_f32_e32 v34, v34, v39
	v_min_f32_e32 v39, 0, v34
	v_mul_f32_e64 v34, |v34|, s94
	v_exp_f32_e32 v34, v34
	s_nop 0
	v_add_f32_e32 v34, 1.0, v34
	v_cmp_gt_f32_e64 s[0:1], s48, v34
	s_nop 1
	v_cndmask_b32_e64 v40, 0, 32, s[0:1]
	v_ldexp_f32 v34, v34, v40
	v_log_f32_e32 v34, v34
	s_nop 0
	v_mul_f32_e32 v40, 0x3f317217, v34
	v_fma_f32 v40, v34, s49, -v40
	v_fmac_f32_e32 v40, 0x3377d1cf, v34
	v_fmac_f32_e32 v40, 0x3f317217, v34
	v_cmp_lt_f32_e64 s[38:39], |v34|, s36
	s_nop 1
	v_cndmask_b32_e64 v34, v34, v40, s[38:39]
	v_cndmask_b32_e64 v40, 0, v192, s[0:1]
	v_sub_f32_e32 v34, v34, v40
	v_sub_f32_e32 v34, v39, v34
	global_load_dword v39, v[8:9], off offset:32
	global_load_dword v40, v[8:9], off offset:48
	global_load_dword v41, v[20:21], off offset:32
	global_load_dword v172, v[20:21], off offset:48
	global_load_dword v42, v[10:11], off offset:32
	global_load_dword v173, v[10:11], off offset:48
	global_load_dword v43, v[12:13], off offset:32
	global_load_dword v174, v[12:13], off offset:48
	global_load_dword v44, v[14:15], off offset:32
	global_load_dword v175, v[14:15], off offset:48
	global_load_dword v45, v[16:17], off offset:32
	global_load_dword v176, v[16:17], off offset:48
	global_load_dword v46, v[18:19], off offset:32
	global_load_dword v177, v[18:19], off offset:48
	global_load_dword v47, v[22:23], off offset:32
	global_load_dword v178, v[22:23], off offset:48
	v_add_f32_e32 v34, 0, v34
	s_waitcnt vmcnt(0) lgkmcnt(0)
	v_add_f32_e32 v40, v58, v40
	v_add_f32_e32 v40, v40, v172
	s_waitcnt vmcnt(0) lgkmcnt(0)
	v_add_f32_e32 v40, v40, v173
	s_waitcnt vmcnt(0) lgkmcnt(0)
	v_add_f32_e32 v40, v40, v174
	s_waitcnt vmcnt(0) lgkmcnt(0)
	v_add_f32_e32 v40, v40, v175
	s_waitcnt vmcnt(0) lgkmcnt(0)
	v_add_f32_e32 v40, v40, v176
	s_waitcnt vmcnt(0) lgkmcnt(0)
	v_add_f32_e32 v40, v40, v177
	s_waitcnt vmcnt(0) lgkmcnt(0)
	v_add_f32_e32 v40, v40, v178
	v_min_f32_e32 v48, 0, v40
	v_mul_f32_e64 v40, |v40|, s94
	v_exp_f32_e32 v40, v40
	s_nop 0
	v_add_f32_e32 v40, 1.0, v40
	v_cmp_gt_f32_e64 s[0:1], s48, v40
	s_nop 1
	v_cndmask_b32_e64 v49, 0, 32, s[0:1]
	v_ldexp_f32 v40, v40, v49
	v_log_f32_e32 v40, v40
	s_nop 0
	v_mul_f32_e32 v49, 0x3f317217, v40
	v_fma_f32 v49, v40, s49, -v49
	v_fmac_f32_e32 v49, 0x3377d1cf, v40
	v_fmac_f32_e32 v49, 0x3f317217, v40
	v_cmp_lt_f32_e64 s[38:39], |v40|, s36
	s_nop 1
	v_cndmask_b32_e64 v40, v40, v49, s[38:39]
	v_cndmask_b32_e64 v49, 0, v192, s[0:1]
	v_sub_f32_e32 v40, v40, v49
	v_sub_f32_e32 v40, v48, v40
	global_load_dword v48, v[8:9], off offset:64
	global_load_dword v49, v[8:9], off offset:80
	global_load_dword v50, v[20:21], off offset:64
	global_load_dword v172, v[20:21], off offset:80
	global_load_dword v51, v[10:11], off offset:64
	global_load_dword v173, v[10:11], off offset:80
	global_load_dword v52, v[12:13], off offset:64
	global_load_dword v174, v[12:13], off offset:80
	global_load_dword v53, v[14:15], off offset:64
	global_load_dword v175, v[14:15], off offset:80
	global_load_dword v54, v[16:17], off offset:64
	global_load_dword v176, v[16:17], off offset:80
	global_load_dword v55, v[18:19], off offset:64
	global_load_dword v177, v[18:19], off offset:80
	global_load_dword v56, v[22:23], off offset:64
	global_load_dword v178, v[22:23], off offset:80
	v_add_f32_e32 v40, v34, v40
	s_waitcnt vmcnt(0) lgkmcnt(0)
; __device__ __forceinline__ float logsig(float x) { return fminf(x, 0.f) - __logf(1.f + __expf(-fabsf(x))); }
; __device__ void gate_scan(const Ctx& p) {
;     ...
; #pragma unroll
;     for (int e = 0; e < 16; ++e) {
;       long tok = (long)b * SEQ + tid * 16 + e;
;       float si = bi, sf = bf;
; #pragma unroll
;       for (int cgp = 0; cgp < 8; ++cgp) {
;         si += gpart[((long)cgp * NTOK + tok) * 8 + h];
;         sf += gpart[((long)cgp * NTOK + tok) * 8 + 4 + h];
;       }
;       ip[e] = si;
;       run += logsig(sf);
;       lf[e] = run;
;     }
	v_add_f32_e32 v49, v58, v49
	v_add_f32_e32 v49, v49, v172
	s_waitcnt vmcnt(0) lgkmcnt(0)
	v_add_f32_e32 v49, v49, v173
	s_waitcnt vmcnt(0) lgkmcnt(0)
	v_add_f32_e32 v49, v49, v174
	s_waitcnt vmcnt(0) lgkmcnt(0)
	v_add_f32_e32 v49, v49, v175
	s_waitcnt vmcnt(0) lgkmcnt(0)
	v_add_f32_e32 v49, v49, v176
	s_waitcnt vmcnt(0) lgkmcnt(0)
	v_add_f32_e32 v49, v49, v177
	s_waitcnt vmcnt(0) lgkmcnt(0)
	v_add_f32_e32 v49, v49, v178
	v_min_f32_e32 v57, 0, v49
	v_mul_f32_e64 v49, |v49|, s94
	v_exp_f32_e32 v49, v49
	s_nop 0
	v_add_f32_e32 v49, 1.0, v49
	v_cmp_gt_f32_e64 s[0:1], s48, v49
	s_nop 1
	v_cndmask_b32_e64 v59, 0, 32, s[0:1]
	v_ldexp_f32 v49, v49, v59
	v_log_f32_e32 v49, v49
	s_nop 0
	v_mul_f32_e32 v59, 0x3f317217, v49
	v_fma_f32 v59, v49, s49, -v59
	v_fmac_f32_e32 v59, 0x3377d1cf, v49
	v_fmac_f32_e32 v59, 0x3f317217, v49
	v_cmp_lt_f32_e64 s[38:39], |v49|, s36
	s_nop 1
	v_cndmask_b32_e64 v49, v49, v59, s[38:39]
	v_cndmask_b32_e64 v59, 0, v192, s[0:1]
	v_sub_f32_e32 v49, v49, v59
	v_sub_f32_e32 v49, v57, v49
	global_load_dword v57, v[8:9], off offset:96
	global_load_dword v59, v[8:9], off offset:112
	global_load_dword v60, v[20:21], off offset:96
	global_load_dword v172, v[20:21], off offset:112
	global_load_dword v61, v[10:11], off offset:96
	global_load_dword v173, v[10:11], off offset:112
	global_load_dword v62, v[12:13], off offset:96
	global_load_dword v174, v[12:13], off offset:112
	global_load_dword v63, v[14:15], off offset:96
	global_load_dword v175, v[14:15], off offset:112
	global_load_dword v64, v[16:17], off offset:96
	global_load_dword v176, v[16:17], off offset:112
	global_load_dword v65, v[18:19], off offset:96
	global_load_dword v177, v[18:19], off offset:112
	global_load_dword v66, v[22:23], off offset:96
	global_load_dword v178, v[22:23], off offset:112
	v_add_f32_e32 v49, v40, v49
	s_waitcnt vmcnt(0) lgkmcnt(0)
	v_add_f32_e32 v59, v58, v59
	v_add_f32_e32 v59, v59, v172
	s_waitcnt vmcnt(0) lgkmcnt(0)
	v_add_f32_e32 v59, v59, v173
	s_waitcnt vmcnt(0) lgkmcnt(0)
	v_add_f32_e32 v59, v59, v174
	s_waitcnt vmcnt(0) lgkmcnt(0)
	v_add_f32_e32 v59, v59, v175
	s_waitcnt vmcnt(0) lgkmcnt(0)
	v_add_f32_e32 v59, v59, v176
	s_waitcnt vmcnt(0) lgkmcnt(0)
	v_add_f32_e32 v59, v59, v177
	s_waitcnt vmcnt(0) lgkmcnt(0)
	v_add_f32_e32 v59, v59, v178
	v_min_f32_e32 v67, 0, v59
	v_mul_f32_e64 v59, |v59|, s94
	v_exp_f32_e32 v59, v59
	s_nop 0
	v_add_f32_e32 v59, 1.0, v59
	v_cmp_gt_f32_e64 s[0:1], s48, v59
	s_nop 1
	v_cndmask_b32_e64 v68, 0, 32, s[0:1]
	v_ldexp_f32 v59, v59, v68
	v_log_f32_e32 v59, v59
	s_nop 0
	v_mul_f32_e32 v68, 0x3f317217, v59
	v_fma_f32 v68, v59, s49, -v68
	v_fmac_f32_e32 v68, 0x3377d1cf, v59
	v_fmac_f32_e32 v68, 0x3f317217, v59
	v_cmp_lt_f32_e64 s[38:39], |v59|, s36
	s_nop 1
	v_cndmask_b32_e64 v59, v59, v68, s[38:39]
	v_cndmask_b32_e64 v68, 0, v192, s[0:1]
	v_sub_f32_e32 v59, v59, v68
	v_sub_f32_e32 v59, v67, v59
	global_load_dword v67, v[8:9], off offset:128
	global_load_dword v68, v[8:9], off offset:144
	global_load_dword v172, v[20:21], off offset:144
	global_load_dword v173, v[10:11], off offset:144
	global_load_dword v174, v[12:13], off offset:144
	global_load_dword v175, v[14:15], off offset:144
	global_load_dword v176, v[16:17], off offset:144
	global_load_dword v177, v[18:19], off offset:144
	global_load_dword v178, v[22:23], off offset:144
	v_add_f32_e32 v59, v49, v59
	s_waitcnt vmcnt(0) lgkmcnt(0)
	v_add_f32_e32 v69, v58, v68
	global_load_dword v68, v[20:21], off offset:128
	s_waitcnt vmcnt(0) lgkmcnt(0)
	v_add_f32_e32 v70, v69, v172
	global_load_dword v69, v[10:11], off offset:128
	s_waitcnt vmcnt(0) lgkmcnt(0)
	v_add_f32_e32 v71, v70, v173
	global_load_dword v70, v[12:13], off offset:128
	s_waitcnt vmcnt(0) lgkmcnt(0)
	v_add_f32_e32 v72, v71, v174
	global_load_dword v71, v[14:15], off offset:128
	s_waitcnt vmcnt(0) lgkmcnt(0)
	v_add_f32_e32 v73, v72, v175
	global_load_dword v72, v[16:17], off offset:128
	s_waitcnt vmcnt(0) lgkmcnt(0)
	v_add_f32_e32 v74, v73, v176
	global_load_dword v73, v[18:19], off offset:128
	s_waitcnt vmcnt(0) lgkmcnt(0)
	v_add_f32_e32 v75, v74, v177
	global_load_dword v74, v[22:23], off offset:128
	s_waitcnt vmcnt(0) lgkmcnt(0)
	v_add_f32_e32 v75, v75, v178
	v_min_f32_e32 v76, 0, v75
	v_mul_f32_e64 v75, |v75|, s94
	v_exp_f32_e32 v75, v75
	s_nop 0
	v_add_f32_e32 v75, 1.0, v75
	v_cmp_gt_f32_e64 s[0:1], s48, v75
	s_nop 1
	v_cndmask_b32_e64 v77, 0, 32, s[0:1]
	v_ldexp_f32 v75, v75, v77
	v_log_f32_e32 v75, v75
	s_nop 0
	v_mul_f32_e32 v77, 0x3f317217, v75
	v_fma_f32 v77, v75, s49, -v77
	v_fmac_f32_e32 v77, 0x3377d1cf, v75
	v_fmac_f32_e32 v77, 0x3f317217, v75
	v_cmp_lt_f32_e64 s[38:39], |v75|, s36
	s_nop 1
	v_cndmask_b32_e64 v75, v75, v77, s[38:39]
	v_cndmask_b32_e64 v77, 0, v192, s[0:1]
	v_sub_f32_e32 v75, v75, v77
	v_sub_f32_e32 v75, v76, v75
	global_load_dword v76, v[8:9], off offset:160
	global_load_dword v77, v[8:9], off offset:176
	global_load_dword v172, v[20:21], off offset:176
	global_load_dword v173, v[10:11], off offset:176
	global_load_dword v80, v[12:13], off offset:160
	global_load_dword v174, v[12:13], off offset:176
	global_load_dword v81, v[14:15], off offset:160
	global_load_dword v175, v[14:15], off offset:176
	global_load_dword v82, v[16:17], off offset:160
	global_load_dword v176, v[16:17], off offset:176
	global_load_dword v83, v[18:19], off offset:160
	global_load_dword v177, v[18:19], off offset:176
	global_load_dword v84, v[22:23], off offset:160
	global_load_dword v178, v[22:23], off offset:176
	v_add_f32_e32 v75, v59, v75
	s_waitcnt vmcnt(0) lgkmcnt(0)
	v_add_f32_e32 v78, v58, v77
	global_load_dword v77, v[20:21], off offset:160
	s_waitcnt vmcnt(0) lgkmcnt(0)
; __device__ __forceinline__ float logsig(float x) { return fminf(x, 0.f) - __logf(1.f + __expf(-fabsf(x))); }
; __device__ void gate_scan(const Ctx& p) {
;     ...
; #pragma unroll
;     for (int e = 0; e < 16; ++e) {
;       long tok = (long)b * SEQ + tid * 16 + e;
;       float si = bi, sf = bf;
; #pragma unroll
;       for (int cgp = 0; cgp < 8; ++cgp) {
;         si += gpart[((long)cgp * NTOK + tok) * 8 + h];
;         sf += gpart[((long)cgp * NTOK + tok) * 8 + 4 + h];
;       }
;       ip[e] = si;
;       run += logsig(sf);
;       lf[e] = run;
;     }
	v_add_f32_e32 v79, v78, v172
	global_load_dword v78, v[10:11], off offset:160
	s_waitcnt vmcnt(0) lgkmcnt(0)
	v_add_f32_e32 v79, v79, v173
	s_waitcnt vmcnt(0) lgkmcnt(0)
	v_add_f32_e32 v79, v79, v174
	s_waitcnt vmcnt(0) lgkmcnt(0)
	v_add_f32_e32 v79, v79, v175
	s_waitcnt vmcnt(0) lgkmcnt(0)
	v_add_f32_e32 v79, v79, v176
	s_waitcnt vmcnt(0) lgkmcnt(0)
	v_add_f32_e32 v79, v79, v177
	s_waitcnt vmcnt(0) lgkmcnt(0)
	v_add_f32_e32 v79, v79, v178
	v_min_f32_e32 v85, 0, v79
	v_mul_f32_e64 v79, |v79|, s94
	v_exp_f32_e32 v79, v79
	s_nop 0
	v_add_f32_e32 v79, 1.0, v79
	v_cmp_gt_f32_e64 s[0:1], s48, v79
	s_nop 1
	v_cndmask_b32_e64 v86, 0, 32, s[0:1]
	v_ldexp_f32 v79, v79, v86
	v_log_f32_e32 v79, v79
	s_nop 0
	v_mul_f32_e32 v86, 0x3f317217, v79
	v_fma_f32 v86, v79, s49, -v86
	v_fmac_f32_e32 v86, 0x3377d1cf, v79
	v_fmac_f32_e32 v86, 0x3f317217, v79
	v_cmp_lt_f32_e64 s[38:39], |v79|, s36
	s_nop 1
	v_cndmask_b32_e64 v79, v79, v86, s[38:39]
	v_cndmask_b32_e64 v86, 0, v192, s[0:1]
	v_sub_f32_e32 v79, v79, v86
	v_sub_f32_e32 v79, v85, v79
	global_load_dword v85, v[8:9], off offset:192
	global_load_dword v86, v[8:9], off offset:208
	global_load_dword v87, v[20:21], off offset:192
	global_load_dword v172, v[20:21], off offset:208
	global_load_dword v88, v[10:11], off offset:192
	global_load_dword v173, v[10:11], off offset:208
	global_load_dword v89, v[12:13], off offset:192
	global_load_dword v174, v[12:13], off offset:208
	global_load_dword v90, v[14:15], off offset:192
	global_load_dword v175, v[14:15], off offset:208
	global_load_dword v91, v[16:17], off offset:192
	global_load_dword v176, v[16:17], off offset:208
	global_load_dword v92, v[18:19], off offset:192
	global_load_dword v177, v[18:19], off offset:208
	global_load_dword v93, v[22:23], off offset:192
	global_load_dword v178, v[22:23], off offset:208
	v_add_f32_e32 v79, v75, v79
	s_waitcnt vmcnt(0) lgkmcnt(0)
	v_add_f32_e32 v86, v58, v86
	v_add_f32_e32 v86, v86, v172
	s_waitcnt vmcnt(0) lgkmcnt(0)
	v_add_f32_e32 v86, v86, v173
	s_waitcnt vmcnt(0) lgkmcnt(0)
	v_add_f32_e32 v86, v86, v174
	s_waitcnt vmcnt(0) lgkmcnt(0)
	v_add_f32_e32 v86, v86, v175
	s_waitcnt vmcnt(0) lgkmcnt(0)
	v_add_f32_e32 v86, v86, v176
	s_waitcnt vmcnt(0) lgkmcnt(0)
	v_add_f32_e32 v86, v86, v177
	s_waitcnt vmcnt(0) lgkmcnt(0)
	v_add_f32_e32 v86, v86, v178
	v_min_f32_e32 v94, 0, v86
	v_mul_f32_e64 v86, |v86|, s94
	v_exp_f32_e32 v86, v86
	s_nop 0
	v_add_f32_e32 v86, 1.0, v86
	v_cmp_gt_f32_e64 s[0:1], s48, v86
	s_nop 1
	v_cndmask_b32_e64 v95, 0, 32, s[0:1]
	v_ldexp_f32 v86, v86, v95
	v_log_f32_e32 v86, v86
	s_nop 0
	v_mul_f32_e32 v95, 0x3f317217, v86
	v_fma_f32 v95, v86, s49, -v95
	v_fmac_f32_e32 v95, 0x3377d1cf, v86
	v_fmac_f32_e32 v95, 0x3f317217, v86
	v_cmp_lt_f32_e64 s[38:39], |v86|, s36
	s_nop 1
	v_cndmask_b32_e64 v86, v86, v95, s[38:39]
	v_cndmask_b32_e64 v95, 0, v192, s[0:1]
	v_sub_f32_e32 v86, v86, v95
	v_sub_f32_e32 v86, v94, v86
	global_load_dword v94, v[8:9], off offset:224
	global_load_dword v95, v[8:9], off offset:240
	global_load_dword v172, v[20:21], off offset:240
	global_load_dword v173, v[10:11], off offset:240
	global_load_dword v174, v[12:13], off offset:240
	global_load_dword v175, v[14:15], off offset:240
	global_load_dword v100, v[16:17], off offset:224
	global_load_dword v176, v[16:17], off offset:240
	global_load_dword v101, v[18:19], off offset:224
	global_load_dword v177, v[18:19], off offset:240
	global_load_dword v102, v[22:23], off offset:224
	global_load_dword v178, v[22:23], off offset:240
	v_add_f32_e32 v86, v79, v86
	s_waitcnt vmcnt(0) lgkmcnt(0)
	v_add_f32_e32 v96, v58, v95
	global_load_dword v95, v[20:21], off offset:224
	s_waitcnt vmcnt(0) lgkmcnt(0)
	v_add_f32_e32 v97, v96, v172
	global_load_dword v96, v[10:11], off offset:224
	s_waitcnt vmcnt(0) lgkmcnt(0)
	v_add_f32_e32 v98, v97, v173
	global_load_dword v97, v[12:13], off offset:224
	s_waitcnt vmcnt(0) lgkmcnt(0)
	v_add_f32_e32 v99, v98, v174
	global_load_dword v98, v[14:15], off offset:224
	s_waitcnt vmcnt(0) lgkmcnt(0)
	v_add_f32_e32 v99, v99, v175
	s_waitcnt vmcnt(0) lgkmcnt(0)
	v_add_f32_e32 v99, v99, v176
	s_waitcnt vmcnt(0) lgkmcnt(0)
	v_add_f32_e32 v99, v99, v177
	s_waitcnt vmcnt(0) lgkmcnt(0)
	v_add_f32_e32 v99, v99, v178
	v_min_f32_e32 v103, 0, v99
	v_mul_f32_e64 v99, |v99|, s94
	v_exp_f32_e32 v99, v99
	s_nop 0
	v_add_f32_e32 v99, 1.0, v99
	v_cmp_gt_f32_e64 s[0:1], s48, v99
	s_nop 1
	v_cndmask_b32_e64 v104, 0, 32, s[0:1]
	v_ldexp_f32 v99, v99, v104
	v_log_f32_e32 v99, v99
	s_nop 0
	v_mul_f32_e32 v104, 0x3f317217, v99
	v_fma_f32 v104, v99, s49, -v104
	v_fmac_f32_e32 v104, 0x3377d1cf, v99
	v_fmac_f32_e32 v104, 0x3f317217, v99
	v_cmp_lt_f32_e64 s[38:39], |v99|, s36
	s_nop 1
	v_cndmask_b32_e64 v99, v99, v104, s[38:39]
	v_cndmask_b32_e64 v104, 0, v192, s[0:1]
	v_sub_f32_e32 v99, v99, v104
	v_sub_f32_e32 v99, v103, v99
	global_load_dword v103, v[8:9], off offset:256
	global_load_dword v104, v[8:9], off offset:272
	global_load_dword v172, v[20:21], off offset:272
	global_load_dword v173, v[10:11], off offset:272
	global_load_dword v174, v[12:13], off offset:272
	global_load_dword v175, v[14:15], off offset:272
	global_load_dword v176, v[16:17], off offset:272
	global_load_dword v110, v[18:19], off offset:256
	global_load_dword v177, v[18:19], off offset:272
	global_load_dword v111, v[22:23], off offset:256
	global_load_dword v178, v[22:23], off offset:272
	v_add_f32_e32 v99, v86, v99
	s_waitcnt vmcnt(0) lgkmcnt(0)
	v_add_f32_e32 v105, v58, v104
	global_load_dword v104, v[20:21], off offset:256
	s_waitcnt vmcnt(0) lgkmcnt(0)
	v_add_f32_e32 v106, v105, v172
	global_load_dword v105, v[10:11], off offset:256
	s_waitcnt vmcnt(0) lgkmcnt(0)
; __device__ __forceinline__ float logsig(float x) { return fminf(x, 0.f) - __logf(1.f + __expf(-fabsf(x))); }
; __device__ void gate_scan(const Ctx& p) {
;     ...
; #pragma unroll
;     for (int e = 0; e < 16; ++e) {
;       long tok = (long)b * SEQ + tid * 16 + e;
;       float si = bi, sf = bf;
; #pragma unroll
;       for (int cgp = 0; cgp < 8; ++cgp) {
;         si += gpart[((long)cgp * NTOK + tok) * 8 + h];
;         sf += gpart[((long)cgp * NTOK + tok) * 8 + 4 + h];
;       }
;       ip[e] = si;
;       run += logsig(sf);
;       lf[e] = run;
;     }
	v_add_f32_e32 v107, v106, v173
	global_load_dword v106, v[12:13], off offset:256
	s_waitcnt vmcnt(0) lgkmcnt(0)
	v_add_f32_e32 v108, v107, v174
	global_load_dword v107, v[14:15], off offset:256
	s_waitcnt vmcnt(0) lgkmcnt(0)
	v_add_f32_e32 v109, v108, v175
	global_load_dword v108, v[16:17], off offset:256
	s_waitcnt vmcnt(0) lgkmcnt(0)
	v_add_f32_e32 v109, v109, v176
	s_waitcnt vmcnt(0) lgkmcnt(0)
	v_add_f32_e32 v109, v109, v177
	s_waitcnt vmcnt(0) lgkmcnt(0)
	v_add_f32_e32 v109, v109, v178
	v_min_f32_e32 v112, 0, v109
	v_mul_f32_e64 v109, |v109|, s94
	v_exp_f32_e32 v109, v109
	s_nop 0
	v_add_f32_e32 v109, 1.0, v109
	v_cmp_gt_f32_e64 s[0:1], s48, v109
	s_nop 1
	v_cndmask_b32_e64 v113, 0, 32, s[0:1]
	v_ldexp_f32 v109, v109, v113
	v_log_f32_e32 v109, v109
	s_nop 0
	v_mul_f32_e32 v113, 0x3f317217, v109
	v_fma_f32 v113, v109, s49, -v113
	v_fmac_f32_e32 v113, 0x3377d1cf, v109
	v_fmac_f32_e32 v113, 0x3f317217, v109
	v_cmp_lt_f32_e64 s[38:39], |v109|, s36
	s_nop 1
	v_cndmask_b32_e64 v109, v109, v113, s[38:39]
	v_cndmask_b32_e64 v113, 0, v192, s[0:1]
	v_sub_f32_e32 v109, v109, v113
	v_sub_f32_e32 v109, v112, v109
	global_load_dword v112, v[8:9], off offset:288
	global_load_dword v113, v[8:9], off offset:304
	global_load_dword v172, v[20:21], off offset:304
	global_load_dword v173, v[10:11], off offset:304
	global_load_dword v116, v[12:13], off offset:288
	global_load_dword v174, v[12:13], off offset:304
	global_load_dword v117, v[14:15], off offset:288
	global_load_dword v175, v[14:15], off offset:304
	global_load_dword v118, v[16:17], off offset:288
	global_load_dword v176, v[16:17], off offset:304
	global_load_dword v119, v[18:19], off offset:288
	global_load_dword v177, v[18:19], off offset:304
	global_load_dword v120, v[22:23], off offset:288
	global_load_dword v178, v[22:23], off offset:304
	v_add_f32_e32 v109, v99, v109
	s_waitcnt vmcnt(0) lgkmcnt(0)
	v_add_f32_e32 v114, v58, v113
	global_load_dword v113, v[20:21], off offset:288
	s_waitcnt vmcnt(0) lgkmcnt(0)
	v_add_f32_e32 v115, v114, v172
	global_load_dword v114, v[10:11], off offset:288
	s_waitcnt vmcnt(0) lgkmcnt(0)
	v_add_f32_e32 v115, v115, v173
	s_waitcnt vmcnt(0) lgkmcnt(0)
	v_add_f32_e32 v115, v115, v174
	s_waitcnt vmcnt(0) lgkmcnt(0)
	v_add_f32_e32 v115, v115, v175
	s_waitcnt vmcnt(0) lgkmcnt(0)
	v_add_f32_e32 v115, v115, v176
	s_waitcnt vmcnt(0) lgkmcnt(0)
	v_add_f32_e32 v115, v115, v177
	s_waitcnt vmcnt(0) lgkmcnt(0)
	v_add_f32_e32 v115, v115, v178
	v_min_f32_e32 v121, 0, v115
	v_mul_f32_e64 v115, |v115|, s94
	v_exp_f32_e32 v115, v115
	s_nop 0
	v_add_f32_e32 v115, 1.0, v115
	v_cmp_gt_f32_e64 s[0:1], s48, v115
	s_nop 1
	v_cndmask_b32_e64 v122, 0, 32, s[0:1]
	v_ldexp_f32 v115, v115, v122
	v_log_f32_e32 v115, v115
	s_nop 0
	v_mul_f32_e32 v122, 0x3f317217, v115
	v_fma_f32 v122, v115, s49, -v122
	v_fmac_f32_e32 v122, 0x3377d1cf, v115
	v_fmac_f32_e32 v122, 0x3f317217, v115
	v_cmp_lt_f32_e64 s[38:39], |v115|, s36
	s_nop 1
	v_cndmask_b32_e64 v115, v115, v122, s[38:39]
	v_cndmask_b32_e64 v122, 0, v192, s[0:1]
	v_sub_f32_e32 v115, v115, v122
	v_sub_f32_e32 v115, v121, v115
	global_load_dword v121, v[8:9], off offset:320
	global_load_dword v122, v[8:9], off offset:336
	global_load_dword v123, v[20:21], off offset:320
	global_load_dword v172, v[20:21], off offset:336
	global_load_dword v124, v[10:11], off offset:320
	global_load_dword v173, v[10:11], off offset:336
	global_load_dword v125, v[12:13], off offset:320
	global_load_dword v174, v[12:13], off offset:336
	global_load_dword v126, v[14:15], off offset:320
	global_load_dword v175, v[14:15], off offset:336
	global_load_dword v127, v[16:17], off offset:320
	global_load_dword v176, v[16:17], off offset:336
	global_load_dword v128, v[18:19], off offset:320
	global_load_dword v177, v[18:19], off offset:336
	global_load_dword v129, v[22:23], off offset:320
	global_load_dword v178, v[22:23], off offset:336
	v_add_f32_e32 v115, v109, v115
	s_waitcnt vmcnt(0) lgkmcnt(0)
	v_add_f32_e32 v122, v58, v122
	v_add_f32_e32 v122, v122, v172
	s_waitcnt vmcnt(0) lgkmcnt(0)
	v_add_f32_e32 v122, v122, v173
	s_waitcnt vmcnt(0) lgkmcnt(0)
	v_add_f32_e32 v122, v122, v174
	s_waitcnt vmcnt(0) lgkmcnt(0)
	v_add_f32_e32 v122, v122, v175
	s_waitcnt vmcnt(0) lgkmcnt(0)
	v_add_f32_e32 v122, v122, v176
	s_waitcnt vmcnt(0) lgkmcnt(0)
	v_add_f32_e32 v122, v122, v177
	s_waitcnt vmcnt(0) lgkmcnt(0)
	v_add_f32_e32 v122, v122, v178
	v_min_f32_e32 v130, 0, v122
	v_mul_f32_e64 v122, |v122|, s94
	v_exp_f32_e32 v122, v122
	s_nop 0
	v_add_f32_e32 v122, 1.0, v122
	v_cmp_gt_f32_e64 s[0:1], s48, v122
	s_nop 1
	v_cndmask_b32_e64 v131, 0, 32, s[0:1]
	v_ldexp_f32 v122, v122, v131
	v_log_f32_e32 v122, v122
	s_nop 0
	v_mul_f32_e32 v131, 0x3f317217, v122
	v_fma_f32 v131, v122, s49, -v131
	v_fmac_f32_e32 v131, 0x3377d1cf, v122
	v_fmac_f32_e32 v131, 0x3f317217, v122
	v_cmp_lt_f32_e64 s[38:39], |v122|, s36
	s_nop 1
	v_cndmask_b32_e64 v122, v122, v131, s[38:39]
	v_cndmask_b32_e64 v131, 0, v192, s[0:1]
	v_sub_f32_e32 v122, v122, v131
	v_sub_f32_e32 v122, v130, v122
	global_load_dword v130, v[8:9], off offset:352
	global_load_dword v131, v[8:9], off offset:368
	global_load_dword v172, v[20:21], off offset:368
	global_load_dword v173, v[10:11], off offset:368
	global_load_dword v174, v[12:13], off offset:368
	global_load_dword v175, v[14:15], off offset:368
	global_load_dword v136, v[16:17], off offset:352
	global_load_dword v176, v[16:17], off offset:368
	global_load_dword v141, v[18:19], off offset:352
	global_load_dword v177, v[18:19], off offset:368
	global_load_dword v142, v[22:23], off offset:352
	global_load_dword v178, v[22:23], off offset:368
	v_add_f32_e32 v122, v115, v122
	s_waitcnt vmcnt(0) lgkmcnt(0)
; __device__ __forceinline__ float logsig(float x) { return fminf(x, 0.f) - __logf(1.f + __expf(-fabsf(x))); }
; __device__ void gate_scan(const Ctx& p) {
;     ...
; #pragma unroll
;     for (int e = 0; e < 16; ++e) {
;       long tok = (long)b * SEQ + tid * 16 + e;
;       float si = bi, sf = bf;
; #pragma unroll
;       for (int cgp = 0; cgp < 8; ++cgp) {
;         si += gpart[((long)cgp * NTOK + tok) * 8 + h];
;         sf += gpart[((long)cgp * NTOK + tok) * 8 + 4 + h];
;       }
;       ip[e] = si;
;       run += logsig(sf);
;       lf[e] = run;
;     }
	v_add_f32_e32 v132, v58, v131
	global_load_dword v131, v[20:21], off offset:352
	s_waitcnt vmcnt(0) lgkmcnt(0)
	v_add_f32_e32 v133, v132, v172
	global_load_dword v132, v[10:11], off offset:352
	s_waitcnt vmcnt(0) lgkmcnt(0)
	v_add_f32_e32 v134, v133, v173
	global_load_dword v133, v[12:13], off offset:352
	s_waitcnt vmcnt(0) lgkmcnt(0)
	v_add_f32_e32 v135, v134, v174
	global_load_dword v134, v[14:15], off offset:352
	s_waitcnt vmcnt(0) lgkmcnt(0)
	v_add_f32_e32 v135, v135, v175
	s_waitcnt vmcnt(0) lgkmcnt(0)
	v_add_f32_e32 v135, v135, v176
	s_waitcnt vmcnt(0) lgkmcnt(0)
	v_add_f32_e32 v135, v135, v177
	s_waitcnt vmcnt(0) lgkmcnt(0)
	v_add_f32_e32 v135, v135, v178
	v_min_f32_e32 v143, 0, v135
	v_mul_f32_e64 v135, |v135|, s94
	v_exp_f32_e32 v135, v135
	s_nop 0
	v_add_f32_e32 v135, 1.0, v135
	v_cmp_gt_f32_e64 s[0:1], s48, v135
	s_nop 1
	v_cndmask_b32_e64 v144, 0, 32, s[0:1]
	v_ldexp_f32 v135, v135, v144
	v_log_f32_e32 v135, v135
	s_nop 0
	v_mul_f32_e32 v144, 0x3f317217, v135
	v_fma_f32 v144, v135, s49, -v144
	v_fmac_f32_e32 v144, 0x3377d1cf, v135
	v_fmac_f32_e32 v144, 0x3f317217, v135
	v_cmp_lt_f32_e64 s[38:39], |v135|, s36
	s_nop 1
	v_cndmask_b32_e64 v135, v135, v144, s[38:39]
	v_cndmask_b32_e64 v144, 0, v192, s[0:1]
	v_sub_f32_e32 v135, v135, v144
	v_sub_f32_e32 v135, v143, v135
	global_load_dword v143, v[8:9], off offset:384
	global_load_dword v144, v[8:9], off offset:400
	global_load_dword v172, v[20:21], off offset:400
	global_load_dword v173, v[10:11], off offset:400
	global_load_dword v174, v[12:13], off offset:400
	global_load_dword v175, v[14:15], off offset:400
	global_load_dword v176, v[16:17], off offset:400
	global_load_dword v177, v[18:19], off offset:400
	global_load_dword v151, v[22:23], off offset:384
	global_load_dword v178, v[22:23], off offset:400
	v_add_f32_e32 v135, v122, v135
	s_waitcnt vmcnt(0) lgkmcnt(0)
	v_add_f32_e32 v145, v58, v144
	global_load_dword v144, v[20:21], off offset:384
	s_waitcnt vmcnt(0) lgkmcnt(0)
	v_add_f32_e32 v146, v145, v172
	global_load_dword v145, v[10:11], off offset:384
	s_waitcnt vmcnt(0) lgkmcnt(0)
	v_add_f32_e32 v147, v146, v173
	global_load_dword v146, v[12:13], off offset:384
	s_waitcnt vmcnt(0) lgkmcnt(0)
	v_add_f32_e32 v148, v147, v174
	global_load_dword v147, v[14:15], off offset:384
	s_waitcnt vmcnt(0) lgkmcnt(0)
	v_add_f32_e32 v149, v148, v175
	global_load_dword v148, v[16:17], off offset:384
	s_waitcnt vmcnt(0) lgkmcnt(0)
	v_add_f32_e32 v150, v149, v176
	global_load_dword v149, v[18:19], off offset:384
	s_waitcnt vmcnt(0) lgkmcnt(0)
	v_add_f32_e32 v150, v150, v177
	s_waitcnt vmcnt(0) lgkmcnt(0)
	v_add_f32_e32 v150, v150, v178
	v_min_f32_e32 v152, 0, v150
	v_mul_f32_e64 v150, |v150|, s94
	v_exp_f32_e32 v150, v150
	s_nop 0
	v_add_f32_e32 v150, 1.0, v150
	v_cmp_gt_f32_e64 s[0:1], s48, v150
	s_nop 1
	v_cndmask_b32_e64 v153, 0, 32, s[0:1]
	v_ldexp_f32 v150, v150, v153
	v_log_f32_e32 v150, v150
	s_nop 0
	v_mul_f32_e32 v153, 0x3f317217, v150
	v_fma_f32 v153, v150, s49, -v153
	v_fmac_f32_e32 v153, 0x3377d1cf, v150
	v_fmac_f32_e32 v153, 0x3f317217, v150
	v_cmp_lt_f32_e64 s[38:39], |v150|, s36
	s_nop 1
	v_cndmask_b32_e64 v150, v150, v153, s[38:39]
	v_cndmask_b32_e64 v153, 0, v192, s[0:1]
	v_sub_f32_e32 v150, v150, v153
	v_sub_f32_e32 v150, v152, v150
	global_load_dword v152, v[8:9], off offset:416
	global_load_dword v153, v[8:9], off offset:432
	global_load_dword v172, v[20:21], off offset:432
	global_load_dword v173, v[10:11], off offset:432
	global_load_dword v174, v[12:13], off offset:432
	global_load_dword v157, v[14:15], off offset:416
	global_load_dword v175, v[14:15], off offset:432
	global_load_dword v158, v[16:17], off offset:416
	global_load_dword v176, v[16:17], off offset:432
	global_load_dword v159, v[18:19], off offset:416
	global_load_dword v177, v[18:19], off offset:432
	global_load_dword v160, v[22:23], off offset:416
	global_load_dword v178, v[22:23], off offset:432
	v_add_f32_e32 v150, v135, v150
	s_waitcnt vmcnt(0) lgkmcnt(0)
	v_add_f32_e32 v154, v58, v153
	global_load_dword v153, v[20:21], off offset:416
	s_waitcnt vmcnt(0) lgkmcnt(0)
	v_add_f32_e32 v155, v154, v172
	global_load_dword v154, v[10:11], off offset:416
	s_waitcnt vmcnt(0) lgkmcnt(0)
	v_add_f32_e32 v156, v155, v173
	global_load_dword v155, v[12:13], off offset:416
	s_waitcnt vmcnt(0) lgkmcnt(0)
	v_add_f32_e32 v156, v156, v174
	s_waitcnt vmcnt(0) lgkmcnt(0)
	v_add_f32_e32 v156, v156, v175
	s_waitcnt vmcnt(0) lgkmcnt(0)
	v_add_f32_e32 v156, v156, v176
	s_waitcnt vmcnt(0) lgkmcnt(0)
	v_add_f32_e32 v156, v156, v177
	s_waitcnt vmcnt(0) lgkmcnt(0)
; __device__ __forceinline__ float logsig(float x) { return fminf(x, 0.f) - __logf(1.f + __expf(-fabsf(x))); }
; __device__ void gate_scan(const Ctx& p) {
;     ...
; #pragma unroll
;     for (int e = 0; e < 16; ++e) {
;       long tok = (long)b * SEQ + tid * 16 + e;
;       float si = bi, sf = bf;
; #pragma unroll
;       for (int cgp = 0; cgp < 8; ++cgp) {
;         si += gpart[((long)cgp * NTOK + tok) * 8 + h];
;         sf += gpart[((long)cgp * NTOK + tok) * 8 + 4 + h];
;       }
;       ip[e] = si;
;       run += logsig(sf);
;       lf[e] = run;
;     }
;     const int lane = tid & 63, w = tid >> 6;
;     float sc = run;
; #pragma unroll
;     for (int o = 1; o < 64; o <<= 1) { const float t = __shfl_up(sc, o, 64); if (lane >= o) sc += t; }
;     __syncthreads();
;     if (lane == 63) red[w] = sc;
;     __syncthreads();
	v_add_f32_e32 v156, v156, v178
	v_min_f32_e32 v161, 0, v156
	v_mul_f32_e64 v156, |v156|, s94
	v_exp_f32_e32 v156, v156
	s_nop 0
	v_add_f32_e32 v156, 1.0, v156
	v_cmp_gt_f32_e64 s[0:1], s48, v156
	s_nop 1
	v_cndmask_b32_e64 v162, 0, 32, s[0:1]
	v_ldexp_f32 v156, v156, v162
	v_log_f32_e32 v156, v156
	s_nop 0
	v_mul_f32_e32 v162, 0x3f317217, v156
	v_fma_f32 v162, v156, s49, -v162
	v_fmac_f32_e32 v162, 0x3377d1cf, v156
	v_fmac_f32_e32 v162, 0x3f317217, v156
	v_cmp_lt_f32_e64 s[38:39], |v156|, s36
	s_nop 1
	v_cndmask_b32_e64 v156, v156, v162, s[38:39]
	v_cndmask_b32_e64 v162, 0, v192, s[0:1]
	v_sub_f32_e32 v156, v156, v162
	v_sub_f32_e32 v156, v161, v156
	global_load_dword v161, v[8:9], off offset:448
	global_load_dword v162, v[8:9], off offset:464
	global_load_dword v163, v[20:21], off offset:448
	global_load_dword v172, v[20:21], off offset:464
	global_load_dword v164, v[10:11], off offset:448
	global_load_dword v173, v[10:11], off offset:464
	global_load_dword v165, v[12:13], off offset:448
	global_load_dword v174, v[12:13], off offset:464
	global_load_dword v166, v[14:15], off offset:448
	global_load_dword v175, v[14:15], off offset:464
	global_load_dword v167, v[16:17], off offset:448
	global_load_dword v176, v[16:17], off offset:464
	global_load_dword v168, v[18:19], off offset:448
	global_load_dword v177, v[18:19], off offset:464
	global_load_dword v169, v[22:23], off offset:448
	global_load_dword v178, v[22:23], off offset:464
	v_add_f32_e32 v156, v150, v156
	s_waitcnt vmcnt(0) lgkmcnt(0)
	v_add_f32_e32 v162, v58, v162
	v_add_f32_e32 v162, v162, v172
	s_waitcnt vmcnt(0) lgkmcnt(0)
	v_add_f32_e32 v162, v162, v173
	s_waitcnt vmcnt(0) lgkmcnt(0)
	v_add_f32_e32 v162, v162, v174
	s_waitcnt vmcnt(0) lgkmcnt(0)
	v_add_f32_e32 v162, v162, v175
	s_waitcnt vmcnt(0) lgkmcnt(0)
	v_add_f32_e32 v162, v162, v176
	s_waitcnt vmcnt(0) lgkmcnt(0)
	v_add_f32_e32 v162, v162, v177
	s_waitcnt vmcnt(0) lgkmcnt(0)
	v_add_f32_e32 v162, v162, v178
	v_min_f32_e32 v170, 0, v162
	v_mul_f32_e64 v162, |v162|, s94
	v_exp_f32_e32 v162, v162
	s_nop 0
	v_add_f32_e32 v162, 1.0, v162
	v_cmp_gt_f32_e64 s[0:1], s48, v162
	s_nop 1
	v_cndmask_b32_e64 v171, 0, 32, s[0:1]
	v_ldexp_f32 v162, v162, v171
	v_log_f32_e32 v162, v162
	s_nop 0
	v_mul_f32_e32 v171, 0x3f317217, v162
	v_fma_f32 v171, v162, s49, -v171
	v_fmac_f32_e32 v171, 0x3377d1cf, v162
	v_fmac_f32_e32 v171, 0x3f317217, v162
	v_cmp_lt_f32_e64 s[38:39], |v162|, s36
	s_nop 1
	v_cndmask_b32_e64 v162, v162, v171, s[38:39]
	v_cndmask_b32_e64 v171, 0, v192, s[0:1]
	v_sub_f32_e32 v162, v162, v171
	v_sub_f32_e32 v162, v170, v162
	global_load_dword v170, v[8:9], off offset:480
	s_nop 0
	global_load_dword v8, v[8:9], off offset:496
	global_load_dword v172, v[20:21], off offset:496
	global_load_dword v173, v[10:11], off offset:496
	global_load_dword v174, v[12:13], off offset:496
	global_load_dword v175, v[14:15], off offset:496
	global_load_dword v176, v[16:17], off offset:496
	global_load_dword v177, v[18:19], off offset:496
	global_load_dword v178, v[22:23], off offset:496
	v_add_f32_e32 v162, v156, v162
	s_waitcnt vmcnt(0) lgkmcnt(0)
	v_add_f32_e32 v9, v58, v8
	global_load_dword v8, v[20:21], off offset:480
	s_nop 0
	s_waitcnt vmcnt(0) lgkmcnt(0)
	v_add_f32_e32 v20, v9, v172
	global_load_dword v9, v[10:11], off offset:480
	s_nop 0
	s_waitcnt vmcnt(0) lgkmcnt(0)
	v_add_f32_e32 v11, v20, v173
	global_load_dword v10, v[12:13], off offset:480
	s_nop 0
	s_waitcnt vmcnt(0) lgkmcnt(0)
	v_add_f32_e32 v12, v11, v174
	global_load_dword v11, v[14:15], off offset:480
	s_waitcnt vmcnt(0) lgkmcnt(0)
	v_add_f32_e32 v13, v12, v175
	global_load_dword v12, v[16:17], off offset:480
	s_waitcnt vmcnt(0) lgkmcnt(0)
	v_add_f32_e32 v14, v13, v176
	global_load_dword v13, v[18:19], off offset:480
	s_waitcnt vmcnt(0) lgkmcnt(0)
	v_add_f32_e32 v15, v14, v177
	global_load_dword v14, v[22:23], off offset:480
	s_waitcnt lgkmcnt(0)
	s_barrier
	s_waitcnt vmcnt(0)
	v_add_f32_e32 v15, v15, v178
	v_min_f32_e32 v16, 0, v15
	v_mul_f32_e64 v15, |v15|, s94
	v_exp_f32_e32 v15, v15
	s_nop 0
	v_add_f32_e32 v15, 1.0, v15
	v_cmp_gt_f32_e64 s[0:1], s48, v15
	s_nop 1
	v_cndmask_b32_e64 v17, 0, 32, s[0:1]
	v_ldexp_f32 v15, v15, v17
	v_log_f32_e32 v15, v15
	s_nop 0
	v_mul_f32_e32 v17, 0x3f317217, v15
	v_fma_f32 v17, v15, s49, -v17
	v_fmac_f32_e32 v17, 0x3377d1cf, v15
	v_fmac_f32_e32 v17, 0x3f317217, v15
	v_cmp_lt_f32_e64 s[38:39], |v15|, s36
	s_nop 1
	v_cndmask_b32_e64 v15, v15, v17, s[38:39]
	v_cndmask_b32_e64 v17, 0, v192, s[0:1]
	v_sub_f32_e32 v15, v15, v17
	v_sub_f32_e32 v15, v16, v15
	v_add_f32_e32 v58, v162, v15
	ds_bpermute_b32 v15, v24, v58
	s_waitcnt lgkmcnt(0)
	v_add_f32_e32 v15, v58, v15
	v_cndmask_b32_e64 v15, v15, v58, s[4:5]
	ds_bpermute_b32 v16, v25, v15
	s_waitcnt lgkmcnt(0)
	v_add_f32_e32 v16, v15, v16
	v_cndmask_b32_e64 v15, v16, v15, s[6:7]
	ds_bpermute_b32 v16, v26, v15
	s_waitcnt lgkmcnt(0)
	v_add_f32_e32 v16, v15, v16
	v_cndmask_b32_e64 v15, v16, v15, s[8:9]
	ds_bpermute_b32 v16, v27, v15
	s_waitcnt lgkmcnt(0)
	v_add_f32_e32 v16, v15, v16
	v_cndmask_b32_e64 v15, v16, v15, s[10:11]
	ds_bpermute_b32 v16, v28, v15
	s_waitcnt lgkmcnt(0)
	v_add_f32_e32 v16, v15, v16
	v_cndmask_b32_e64 v15, v16, v15, s[12:13]
	ds_bpermute_b32 v16, v29, v15
	s_waitcnt lgkmcnt(0)
	v_add_f32_e32 v16, v15, v16
	s_and_saveexec_b64 s[0:1], vcc
	ds_write_b32 v0, v16
	s_or_b64 exec, exec, s[0:1]
	v_mov_b32_e32 v17, 0
	s_waitcnt lgkmcnt(0)
	s_barrier
	s_and_saveexec_b64 s[0:1], s[16:17]
	s_cbranch_execz .LBB0_44
	ds_read_b32 v17, v203
	s_waitcnt lgkmcnt(0)
	v_add_f32_e32 v17, 0, v17
	s_or_b64 exec, exec, s[0:1]
	s_and_saveexec_b64 s[0:1], s[18:19]
	s_cbranch_execnz .LBB0_45
